# plus: tail-loop QK blocks issue all K-fragment LDS reads up front with counted waits instead of one read+wait per MFMA
# speedup vs baseline: 1.0178x; 1.0076x over previous
.LBB0_678:
	s_add_i32 s57, s61, 64
	s_cmp_le_i32 s57, s40
	s_cselect_b64 s[4:5], -1, 0
	s_and_b64 s[4:5], s[14:15], s[4:5]
	s_andn2_b64 vcc, exec, s[4:5]
	s_cbranch_vccnz .LBB0_681
	v_add_u32_e32 v126, s55, v148
	v_add_u32_e32 v12, s54, v158
	ds_read_b128 v[190:193], v126
	ds_read_b128 v[78:81], v12 offset:43008
	ds_read_b128 v[82:85], v12 offset:43040
	ds_read_b128 v[86:89], v12 offset:43072
	ds_read_b128 v[90:93], v12 offset:43104
	ds_read_b128 v[194:197], v126 offset:4608
	ds_read_b128 v[94:97], v12 offset:43136
	ds_read_b128 v[98:101], v12 offset:43168
	ds_read_b128 v[102:105], v12 offset:43200
	ds_read_b128 v[106:109], v12 offset:43232
	ds_read_b128 v[198:201], v126 offset:32
	ds_read_b128 v[202:205], v126 offset:4640
	ds_read_b128 v[206:209], v126 offset:64
	ds_read_b128 v[210:213], v126 offset:4672
	ds_read_b128 v[214:217], v126 offset:96
	s_add_i32 s4, s61, 0x7f
	s_waitcnt lgkmcnt(10)
	v_mfma_f32_32x32x16_bf16 v[78:93], v[190:193], v[0:3], v[78:93]
	ds_read_b128 v[222:225], v126 offset:4704
	s_cmp_le_i32 s4, s40
	s_waitcnt lgkmcnt(6)
	v_mfma_f32_32x32x16_bf16 v[94:109], v[194:197], v[0:3], v[94:109]
	s_waitcnt lgkmcnt(5)
	v_mfma_f32_32x32x16_bf16 v[78:93], v[198:201], v[4:7], v[78:93]
	s_waitcnt lgkmcnt(4)
	v_mfma_f32_32x32x16_bf16 v[94:109], v[202:205], v[4:7], v[94:109]
	s_waitcnt lgkmcnt(3)
	v_mfma_f32_32x32x16_bf16 v[78:93], v[206:209], v[8:11], v[78:93]
	s_waitcnt lgkmcnt(2)
	v_mfma_f32_32x32x16_bf16 v[94:109], v[210:213], v[8:11], v[94:109]
	s_waitcnt lgkmcnt(1)
	v_mfma_f32_32x32x16_bf16 v[78:93], v[214:217], v[110:113], v[78:93]
	s_waitcnt lgkmcnt(0)
	v_mfma_f32_32x32x16_bf16 v[94:109], v[222:225], v[110:113], v[94:109]
	s_cbranch_scc1 .LBB0_681
	v_add_u32_e32 v12, s61, v156
	v_add_u32_e32 v123, 0x60, v12
	v_add_u32_e32 v122, 64, v12
	v_cmp_le_i32_e32 vcc, v123, v157
	s_nop 6
	v_cndmask_b32_e32 v94, v220, v94, vcc
	v_cmp_lt_i32_e32 vcc, v122, v157
	s_nop 1
	v_cndmask_b32_e32 v79, v220, v79, vcc
	v_cmp_le_i32_e32 vcc, v122, v157
	v_add_u32_e32 v122, 0x61, v12
	s_nop 0
	v_cndmask_b32_e32 v78, v220, v78, vcc
	v_cmp_le_i32_e32 vcc, v122, v157
	v_add_u32_e32 v122, 0x42, v12
	s_nop 0
	v_cndmask_b32_e32 v95, v220, v95, vcc
	v_cmp_le_i32_e32 vcc, v122, v157
	v_add_u32_e32 v122, 0x62, v12
	s_nop 0
	v_cndmask_b32_e32 v80, v220, v80, vcc
	v_cmp_le_i32_e32 vcc, v122, v157
	v_add_u32_e32 v122, 0x43, v12
	s_nop 0
	v_cndmask_b32_e32 v96, v220, v96, vcc
	v_cmp_le_i32_e32 vcc, v122, v157
	v_add_u32_e32 v122, 0x63, v12
	s_nop 0
	v_cndmask_b32_e32 v81, v220, v81, vcc
	v_cmp_le_i32_e32 vcc, v122, v157
	v_add_u32_e32 v122, 0x48, v12
	s_nop 0
	v_cndmask_b32_e32 v97, v220, v97, vcc
	v_cmp_le_i32_e32 vcc, v122, v157
	v_add_u32_e32 v122, 0x68, v12
	s_nop 0
	v_cndmask_b32_e32 v82, v220, v82, vcc
	v_cmp_le_i32_e32 vcc, v122, v157
	v_add_u32_e32 v122, 0x49, v12
	s_nop 0
	v_cndmask_b32_e32 v98, v220, v98, vcc
	v_cmp_le_i32_e32 vcc, v122, v157
	v_add_u32_e32 v122, 0x69, v12
	s_nop 0
	v_cndmask_b32_e32 v83, v220, v83, vcc
	v_cmp_le_i32_e32 vcc, v122, v157
	v_add_u32_e32 v122, 0x4a, v12
	s_nop 0
	v_cndmask_b32_e32 v99, v220, v99, vcc
	v_cmp_le_i32_e32 vcc, v122, v157
	v_add_u32_e32 v122, 0x6a, v12
	s_nop 0
	v_cndmask_b32_e32 v84, v220, v84, vcc
	v_cmp_le_i32_e32 vcc, v122, v157
	v_add_u32_e32 v122, 0x4b, v12
	s_nop 0
	v_cndmask_b32_e32 v100, v220, v100, vcc
	v_cmp_le_i32_e32 vcc, v122, v157
	v_add_u32_e32 v122, 0x6b, v12
	s_nop 0
	v_cndmask_b32_e32 v85, v220, v85, vcc
	v_cmp_le_i32_e32 vcc, v122, v157
	v_add_u32_e32 v122, 0x50, v12
	s_nop 0
	v_cndmask_b32_e32 v101, v220, v101, vcc
	v_cmp_le_i32_e32 vcc, v122, v157
	v_add_u32_e32 v122, 0x70, v12
	s_nop 0
	v_cndmask_b32_e32 v86, v220, v86, vcc
	v_cmp_le_i32_e32 vcc, v122, v157
	v_add_u32_e32 v122, 0x51, v12
	s_nop 0
	v_cndmask_b32_e32 v102, v220, v102, vcc
	v_cmp_le_i32_e32 vcc, v122, v157
	v_add_u32_e32 v122, 0x71, v12
	s_nop 0
	v_cndmask_b32_e32 v87, v220, v87, vcc
	v_cmp_le_i32_e32 vcc, v122, v157
	v_add_u32_e32 v122, 0x52, v12
	s_nop 0
	v_cndmask_b32_e32 v103, v220, v103, vcc
	v_cmp_le_i32_e32 vcc, v122, v157
	v_add_u32_e32 v122, 0x72, v12
	s_nop 0
	v_cndmask_b32_e32 v88, v220, v88, vcc
	v_cmp_le_i32_e32 vcc, v122, v157
	v_add_u32_e32 v122, 0x53, v12
	s_nop 0
	v_cndmask_b32_e32 v104, v220, v104, vcc
	v_cmp_le_i32_e32 vcc, v122, v157
	v_add_u32_e32 v122, 0x73, v12
	s_nop 0
	v_cndmask_b32_e32 v89, v220, v89, vcc
	v_cmp_le_i32_e32 vcc, v122, v157
	v_add_u32_e32 v122, 0x58, v12
	s_nop 0
	v_cndmask_b32_e32 v105, v220, v105, vcc
	v_cmp_le_i32_e32 vcc, v122, v157
	v_add_u32_e32 v122, 0x78, v12
	s_nop 0
	v_cndmask_b32_e32 v90, v220, v90, vcc
	v_cmp_le_i32_e32 vcc, v122, v157
	v_add_u32_e32 v122, 0x59, v12
	s_nop 0
	v_cndmask_b32_e32 v106, v220, v106, vcc
	v_cmp_le_i32_e32 vcc, v122, v157
	v_add_u32_e32 v122, 0x79, v12
	s_nop 0
	v_cndmask_b32_e32 v91, v220, v91, vcc
	v_cmp_le_i32_e32 vcc, v122, v157
	v_add_u32_e32 v122, 0x5a, v12
	s_nop 0
	v_cndmask_b32_e32 v107, v220, v107, vcc
	v_cmp_le_i32_e32 vcc, v122, v157
	v_add_u32_e32 v122, 0x7a, v12
	s_nop 0
	v_cndmask_b32_e32 v92, v220, v92, vcc
	v_cmp_le_i32_e32 vcc, v122, v157
	v_add_u32_e32 v122, 0x5b, v12
	v_add_u32_e32 v12, 0x7b, v12
	v_cndmask_b32_e32 v108, v220, v108, vcc
	v_cmp_le_i32_e32 vcc, v122, v157
	s_nop 1
	v_cndmask_b32_e32 v93, v220, v93, vcc
	v_cmp_le_i32_e32 vcc, v12, v157
	s_nop 1
	v_cndmask_b32_e32 v109, v220, v109, vcc

.LBB0_697:
	s_add_i32 s13, s61, 0x80
	s_cmp_le_i32 s13, s40
	s_cselect_b64 s[16:17], -1, 0
	s_and_b64 s[10:11], s[10:11], s[16:17]
	s_andn2_b64 vcc, exec, s[10:11]
	s_cbranch_vccnz .LBB0_700
	v_add_u32_e32 v126, s58, v148
	v_add_u32_e32 v12, s59, v158
	ds_read_b128 v[190:193], v126
	ds_read_b128 v[46:49], v12 offset:43008
	ds_read_b128 v[50:53], v12 offset:43040
	ds_read_b128 v[54:57], v12 offset:43072
	ds_read_b128 v[58:61], v12 offset:43104
	ds_read_b128 v[194:197], v126 offset:4608
	ds_read_b128 v[62:65], v12 offset:43136
	ds_read_b128 v[66:69], v12 offset:43168
	ds_read_b128 v[70:73], v12 offset:43200
	ds_read_b128 v[74:77], v12 offset:43232
	ds_read_b128 v[198:201], v126 offset:32
	ds_read_b128 v[202:205], v126 offset:4640
	ds_read_b128 v[206:209], v126 offset:64
	ds_read_b128 v[210:213], v126 offset:4672
	ds_read_b128 v[214:217], v126 offset:96
	s_add_i32 s10, s61, 0xbf
	s_waitcnt lgkmcnt(10)
	v_mfma_f32_32x32x16_bf16 v[46:61], v[190:193], v[0:3], v[46:61]
	ds_read_b128 v[222:225], v126 offset:4704
	s_cmp_le_i32 s10, s40
	s_waitcnt lgkmcnt(6)
	v_mfma_f32_32x32x16_bf16 v[62:77], v[194:197], v[0:3], v[62:77]
	s_waitcnt lgkmcnt(5)
	v_mfma_f32_32x32x16_bf16 v[46:61], v[198:201], v[4:7], v[46:61]
	s_waitcnt lgkmcnt(4)
	v_mfma_f32_32x32x16_bf16 v[62:77], v[202:205], v[4:7], v[62:77]
	s_waitcnt lgkmcnt(3)
	v_mfma_f32_32x32x16_bf16 v[46:61], v[206:209], v[8:11], v[46:61]
	s_waitcnt lgkmcnt(2)
	v_mfma_f32_32x32x16_bf16 v[62:77], v[210:213], v[8:11], v[62:77]
	s_waitcnt lgkmcnt(1)
	v_mfma_f32_32x32x16_bf16 v[46:61], v[214:217], v[110:113], v[46:61]
	s_waitcnt lgkmcnt(0)
	v_mfma_f32_32x32x16_bf16 v[62:77], v[222:225], v[110:113], v[62:77]
	s_cbranch_scc1 .LBB0_700
	v_add_u32_e32 v12, s61, v156
	v_add_u32_e32 v123, 0xa0, v12
	v_add_u32_e32 v122, 0x80, v12
	v_cmp_le_i32_e32 vcc, v123, v157
	s_nop 6
	v_cndmask_b32_e32 v62, v220, v62, vcc
	v_cmp_lt_i32_e32 vcc, v122, v157
	s_nop 1
	v_cndmask_b32_e32 v47, v220, v47, vcc
	v_cmp_le_i32_e32 vcc, v122, v157
	v_add_u32_e32 v122, 0xa1, v12
	s_nop 0
	v_cndmask_b32_e32 v46, v220, v46, vcc
	v_cmp_le_i32_e32 vcc, v122, v157
	v_add_u32_e32 v122, 0x82, v12
	s_nop 0
	v_cndmask_b32_e32 v63, v220, v63, vcc
	v_cmp_le_i32_e32 vcc, v122, v157
	v_add_u32_e32 v122, 0xa2, v12
	s_nop 0
	v_cndmask_b32_e32 v48, v220, v48, vcc
	v_cmp_le_i32_e32 vcc, v122, v157
	v_add_u32_e32 v122, 0x83, v12
	s_nop 0
	v_cndmask_b32_e32 v64, v220, v64, vcc
	v_cmp_le_i32_e32 vcc, v122, v157
	v_add_u32_e32 v122, 0xa3, v12
	s_nop 0
	v_cndmask_b32_e32 v49, v220, v49, vcc
	v_cmp_le_i32_e32 vcc, v122, v157
	v_add_u32_e32 v122, 0x88, v12
	s_nop 0
	v_cndmask_b32_e32 v65, v220, v65, vcc
	v_cmp_le_i32_e32 vcc, v122, v157
	v_add_u32_e32 v122, 0xa8, v12
	s_nop 0
	v_cndmask_b32_e32 v50, v220, v50, vcc
	v_cmp_le_i32_e32 vcc, v122, v157
	v_add_u32_e32 v122, 0x89, v12
	s_nop 0
	v_cndmask_b32_e32 v66, v220, v66, vcc
	v_cmp_le_i32_e32 vcc, v122, v157
	v_add_u32_e32 v122, 0xa9, v12
	s_nop 0
	v_cndmask_b32_e32 v51, v220, v51, vcc
	v_cmp_le_i32_e32 vcc, v122, v157
	v_add_u32_e32 v122, 0x8a, v12
	s_nop 0
	v_cndmask_b32_e32 v67, v220, v67, vcc
	v_cmp_le_i32_e32 vcc, v122, v157
	v_add_u32_e32 v122, 0xaa, v12
	s_nop 0
	v_cndmask_b32_e32 v52, v220, v52, vcc
	v_cmp_le_i32_e32 vcc, v122, v157
	v_add_u32_e32 v122, 0x8b, v12
	s_nop 0
	v_cndmask_b32_e32 v68, v220, v68, vcc
	v_cmp_le_i32_e32 vcc, v122, v157
	v_add_u32_e32 v122, 0xab, v12
	s_nop 0
	v_cndmask_b32_e32 v53, v220, v53, vcc
	v_cmp_le_i32_e32 vcc, v122, v157
	v_add_u32_e32 v122, 0x90, v12
	s_nop 0
	v_cndmask_b32_e32 v69, v220, v69, vcc
	v_cmp_le_i32_e32 vcc, v122, v157
	v_add_u32_e32 v122, 0xb0, v12
	s_nop 0
	v_cndmask_b32_e32 v54, v220, v54, vcc
	v_cmp_le_i32_e32 vcc, v122, v157
	v_add_u32_e32 v122, 0x91, v12
	s_nop 0
	v_cndmask_b32_e32 v70, v220, v70, vcc
	v_cmp_le_i32_e32 vcc, v122, v157
	v_add_u32_e32 v122, 0xb1, v12
	s_nop 0
	v_cndmask_b32_e32 v55, v220, v55, vcc
	v_cmp_le_i32_e32 vcc, v122, v157
	v_add_u32_e32 v122, 0x92, v12
	s_nop 0
	v_cndmask_b32_e32 v71, v220, v71, vcc
	v_cmp_le_i32_e32 vcc, v122, v157
	v_add_u32_e32 v122, 0xb2, v12
	s_nop 0
	v_cndmask_b32_e32 v56, v220, v56, vcc
	v_cmp_le_i32_e32 vcc, v122, v157
	v_add_u32_e32 v122, 0x93, v12
	s_nop 0
	v_cndmask_b32_e32 v72, v220, v72, vcc
	v_cmp_le_i32_e32 vcc, v122, v157
	v_add_u32_e32 v122, 0xb3, v12
	s_nop 0
	v_cndmask_b32_e32 v57, v220, v57, vcc
	v_cmp_le_i32_e32 vcc, v122, v157
	v_add_u32_e32 v122, 0x98, v12
	s_nop 0
	v_cndmask_b32_e32 v73, v220, v73, vcc
	v_cmp_le_i32_e32 vcc, v122, v157
	v_add_u32_e32 v122, 0xb8, v12
	s_nop 0
	v_cndmask_b32_e32 v58, v220, v58, vcc
	v_cmp_le_i32_e32 vcc, v122, v157
	v_add_u32_e32 v122, 0x99, v12
	s_nop 0
	v_cndmask_b32_e32 v74, v220, v74, vcc
	v_cmp_le_i32_e32 vcc, v122, v157
	v_add_u32_e32 v122, 0xb9, v12
	s_nop 0
	v_cndmask_b32_e32 v59, v220, v59, vcc
	v_cmp_le_i32_e32 vcc, v122, v157
	v_add_u32_e32 v122, 0x9a, v12
	s_nop 0
	v_cndmask_b32_e32 v75, v220, v75, vcc
	v_cmp_le_i32_e32 vcc, v122, v157
	v_add_u32_e32 v122, 0xba, v12
	s_nop 0
	v_cndmask_b32_e32 v60, v220, v60, vcc
	v_cmp_le_i32_e32 vcc, v122, v157
	v_add_u32_e32 v122, 0x9b, v12
	v_add_u32_e32 v12, 0xbb, v12
	v_cndmask_b32_e32 v76, v220, v76, vcc
	v_cmp_le_i32_e32 vcc, v122, v157
	s_nop 1
	v_cndmask_b32_e32 v61, v220, v61, vcc
	v_cmp_le_i32_e32 vcc, v12, v157
	s_nop 1
	v_cndmask_b32_e32 v77, v220, v77, vcc

.LBB0_747:
	s_add_i32 s40, s25, 64
	s_cmp_le_i32 s40, s39
	s_cselect_b64 s[4:5], -1, 0
	s_and_b64 s[4:5], s[12:13], s[4:5]
	s_andn2_b64 vcc, exec, s[4:5]
	s_cbranch_vccnz .LBB0_749
	ds_read_b128 v[190:193], v162 offset:13312
	ds_read_b128 v[194:197], v162 offset:13344
	ds_read_b128 v[198:201], v162 offset:19968
	ds_read_b128 v[202:205], v162 offset:20000
	ds_read_b128 v[206:209], v162 offset:13376
	ds_read_b128 v[210:213], v162 offset:20032
	ds_read_b128 v[214:217], v162 offset:13408
	ds_read_b128 v[222:225], v162 offset:20064
	ds_read_b128 v[226:229], v162 offset:13440
	ds_read_b128 v[230:233], v162 offset:20096
	ds_read_b128 v[234:237], v162 offset:13472
	ds_read_b128 v[238:241], v162 offset:20128
	s_waitcnt lgkmcnt(11)
	v_mfma_f32_32x32x16_bf16 v[78:93], v[190:193], v[0:3], 0
	s_waitcnt lgkmcnt(10)
	v_mfma_f32_32x32x16_bf16 v[78:93], v[194:197], v[4:7], v[78:93]
	s_waitcnt lgkmcnt(9)
	v_mfma_f32_32x32x16_bf16 v[94:109], v[198:201], v[0:3], 0
	s_waitcnt lgkmcnt(8)
	v_mfma_f32_32x32x16_bf16 v[94:109], v[202:205], v[4:7], v[94:109]
	s_waitcnt lgkmcnt(7)
	v_mfma_f32_32x32x16_bf16 v[78:93], v[206:209], v[8:11], v[78:93]
	s_waitcnt lgkmcnt(6)
	v_mfma_f32_32x32x16_bf16 v[94:109], v[210:213], v[8:11], v[94:109]
	s_waitcnt lgkmcnt(5)
	v_mfma_f32_32x32x16_bf16 v[78:93], v[214:217], v[110:113], v[78:93]
	s_waitcnt lgkmcnt(4)
	v_mfma_f32_32x32x16_bf16 v[94:109], v[222:225], v[110:113], v[94:109]
	s_waitcnt lgkmcnt(3)
	v_mfma_f32_32x32x16_bf16 v[78:93], v[226:229], v[114:117], v[78:93]
	s_waitcnt lgkmcnt(2)
	v_mfma_f32_32x32x16_bf16 v[94:109], v[230:233], v[114:117], v[94:109]
	s_waitcnt lgkmcnt(1)
	v_mfma_f32_32x32x16_bf16 v[78:93], v[234:237], v[118:121], v[78:93]
	s_waitcnt lgkmcnt(0)
	v_mfma_f32_32x32x16_bf16 v[94:109], v[238:241], v[118:121], v[94:109]

.LBB0_765:
	s_addk_i32 s25, 0x80
	s_cmp_le_i32 s25, s39
	s_cselect_b64 s[14:15], -1, 0
	s_and_b64 s[10:11], s[10:11], s[14:15]
	s_andn2_b64 vcc, exec, s[10:11]
	s_cbranch_vccnz .LBB0_767
	ds_read_b128 v[190:193], v162
	ds_read_b128 v[194:197], v162 offset:32
	ds_read_b128 v[198:201], v162 offset:6656
	ds_read_b128 v[202:205], v162 offset:6688
	ds_read_b128 v[206:209], v162 offset:64
	ds_read_b128 v[210:213], v162 offset:6720
	ds_read_b128 v[214:217], v162 offset:96
	ds_read_b128 v[222:225], v162 offset:6752
	ds_read_b128 v[226:229], v162 offset:128
	ds_read_b128 v[230:233], v162 offset:6784
	ds_read_b128 v[234:237], v162 offset:160
	ds_read_b128 v[238:241], v162 offset:6816
	s_waitcnt lgkmcnt(11)
	v_mfma_f32_32x32x16_bf16 v[46:61], v[190:193], v[0:3], 0
	s_waitcnt lgkmcnt(10)
	v_mfma_f32_32x32x16_bf16 v[46:61], v[194:197], v[4:7], v[46:61]
	s_waitcnt lgkmcnt(9)
	v_mfma_f32_32x32x16_bf16 v[62:77], v[198:201], v[0:3], 0
	s_waitcnt lgkmcnt(8)
	v_mfma_f32_32x32x16_bf16 v[62:77], v[202:205], v[4:7], v[62:77]
	s_waitcnt lgkmcnt(7)
	v_mfma_f32_32x32x16_bf16 v[46:61], v[206:209], v[8:11], v[46:61]
	s_waitcnt lgkmcnt(6)
	v_mfma_f32_32x32x16_bf16 v[62:77], v[210:213], v[8:11], v[62:77]
	s_waitcnt lgkmcnt(5)
	v_mfma_f32_32x32x16_bf16 v[46:61], v[214:217], v[110:113], v[46:61]
	s_waitcnt lgkmcnt(4)
	v_mfma_f32_32x32x16_bf16 v[62:77], v[222:225], v[110:113], v[62:77]
	s_waitcnt lgkmcnt(3)
	v_mfma_f32_32x32x16_bf16 v[46:61], v[226:229], v[114:117], v[46:61]
	s_waitcnt lgkmcnt(2)
	v_mfma_f32_32x32x16_bf16 v[62:77], v[230:233], v[114:117], v[62:77]
	s_waitcnt lgkmcnt(1)
	v_mfma_f32_32x32x16_bf16 v[46:61], v[234:237], v[118:121], v[46:61]
	s_waitcnt lgkmcnt(0)
	v_mfma_f32_32x32x16_bf16 v[62:77], v[238:241], v[118:121], v[62:77]
